# same as previous but the static s_setprio 1 goes to waves 0-3 (the LDS-write-heavy waves of the scan phases)
# speedup vs baseline: 1.0006x; 1.0006x over previous
_Z4mega6Params:
	s_load_dwordx8 s[88:95], s[0:1], 0xa0
	s_load_dwordx8 s[4:11], s[0:1], 0x80
	s_load_dword s96, s[0:1], 0xc0
	s_mov_b32 s97, s2
	s_add_u32 s2, s0, 0xc0
	s_addc_u32 s3, s1, 0
	s_waitcnt lgkmcnt(0)
	v_readfirstlane_b32 s98, v0
	s_nop 3
	s_cmpk_ge_u32 s98, 0x100
	s_cbranch_scc1 .Lprio_skip
	s_setprio 1
